# S2 (P2->P4) and S7 (P7->P9) back to full-grid barriers: the Q/K/V/U/Z/G buffers overlay ACT, so other groups must have finished reading first; other hand-offs keep 4-workgroup seams
# baseline (speedup 1.0000x reference)
; __device__ __forceinline__ unsigned xb_ld(unsigned* p)              { return __hip_atomic_load(p, __ATOMIC_RELAXED, __HIP_MEMORY_SCOPE_AGENT); }
; __device__ __forceinline__ unsigned xb_add(unsigned* p, unsigned v) { return __hip_atomic_fetch_add(p, v, __ATOMIC_RELAXED, __HIP_MEMORY_SCOPE_AGENT); }
; #define XB_SPIN(cond, bar) do { unsigned _sp = 0; while (cond) { __builtin_amdgcn_s_sleep(1); \
;     if ((++_sp & 255u) == 0u) { if (xb_ld(&(bar)[XB_TMO])) break; if (_sp > XB_SPIN_CAP) { atomicAdd(&(bar)[XB_TMO], 1u); break; } } } } while (0)
; __device__ __forceinline__ void xcd_barrier(const XcdBarrier& b) {
;     asm volatile("s_waitcnt vmcnt(0)" ::: "memory");
;     __syncthreads();
;     if (threadIdx.x == 0) {
;         unsigned* bar = b.bar;
;         __builtin_amdgcn_s_waitcnt(0);
;         unsigned nloc = b.st[0], nx = b.st[1];
;         if (nloc == 0u) { xcd_barrier_complete(bar, b.x, nloc, nx); b.st[0] = nloc; b.st[1] = nx; }
;         const unsigned old = xb_add(&bar[XB_XSUB(b.x)], 1u);
;         const unsigned gen = old / nloc;
;         if (old + 1u == (gen + 1u) * nloc) {
;             __builtin_amdgcn_fence(__ATOMIC_RELEASE, "agent");
;             asm volatile("s_waitcnt vmcnt(0)" ::: "memory");
;             const unsigned og = xb_add(&bar[XB_TOP], 1u);
;             const unsigned tg = og / nx;
;             if (og + 1u == (tg + 1u) * nx) xb_add(&bar[XB_TOPGEN], 1u);
;             else XB_SPIN(xb_ld(&bar[XB_TOPGEN]) == tg, bar);
;             __builtin_amdgcn_fence(__ATOMIC_ACQUIRE, "agent");
;             xb_add(&bar[XB_XGEN(b.x)], 1u);
;             asm volatile("s_waitcnt vmcnt(0)" ::: "memory");
;         } else {
;             XB_SPIN(xb_ld(&bar[XB_XGEN(b.x)]) == gen, bar);
;             __builtin_amdgcn_fence(__ATOMIC_ACQUIRE, "agent");
;             asm volatile("s_waitcnt vmcnt(0)" ::: "memory");
;         }
;     }
;     __syncthreads();
; }
.LBB0_513:
	s_cmp_gt_i32 s75, 7
	s_cselect_b64 s[0:1], -1, 0
	s_and_b64 s[2:3], s[8:9], s[0:1]
	s_andn2_b64 vcc, exec, s[2:3]
	s_cbranch_vccnz .LBB0_563
	s_waitcnt vmcnt(0)
	v_cmp_eq_u32_e32 vcc, 0, v189
	s_waitcnt vmcnt(0) lgkmcnt(0)
	s_barrier
	s_and_saveexec_b64 s[4:5], vcc
	s_cbranch_execz .LBB0_562
	v_mov_b32_e32 v0, 0x20430
	ds_read_b32 v0, v0
	s_waitcnt lgkmcnt(0)
	v_cmp_ne_u32_e32 vcc, 0, v0
	s_cbranch_vccz .Lseam_slow_5
	v_readlane_b32 s8, v255, 0
	v_readlane_b32 s2, v254, 4
	v_readlane_b32 s3, v254, 5
	s_and_b32 s8, s8, 63
	s_lshl_b32 s8, s8, 2
	s_add_i32 s8, s8, 0x100
	v_mov_b32_e32 v0, s8
	v_mov_b32_e32 v1, 1
	s_mov_b32 s9, 0
	s_nop 2
	global_atomic_add v0, v1, s[2:3]
.Lseam_spin_5:
	global_load_dword v2, v0, s[2:3] sc1
	s_add_i32 s9, s9, 1
	s_waitcnt vmcnt(0)
	v_cmp_gt_u32_e32 vcc, 8, v2
	s_cbranch_vccz .Lseam_done_5
	s_cmp_gt_u32 s9, 30000
	s_cbranch_scc1 .Lseam_done_5
	s_sleep 1
	s_branch .Lseam_spin_5

; __device__ __forceinline__ unsigned xb_ld(unsigned* p)              { return __hip_atomic_load(p, __ATOMIC_RELAXED, __HIP_MEMORY_SCOPE_AGENT); }
; __device__ __forceinline__ unsigned xb_add(unsigned* p, unsigned v) { return __hip_atomic_fetch_add(p, v, __ATOMIC_RELAXED, __HIP_MEMORY_SCOPE_AGENT); }
; #define XB_SPIN(cond, bar) do { unsigned _sp = 0; while (cond) { __builtin_amdgcn_s_sleep(1); \
;     if ((++_sp & 255u) == 0u) { if (xb_ld(&(bar)[XB_TMO])) break; if (_sp > XB_SPIN_CAP) { atomicAdd(&(bar)[XB_TMO], 1u); break; } } } } while (0)
; __device__ __forceinline__ void xcd_barrier(const XcdBarrier& b) {
;     asm volatile("s_waitcnt vmcnt(0)" ::: "memory");
;     __syncthreads();
;     if (threadIdx.x == 0) {
;         unsigned* bar = b.bar;
;         __builtin_amdgcn_s_waitcnt(0);
;         unsigned nloc = b.st[0], nx = b.st[1];
;         if (nloc == 0u) { xcd_barrier_complete(bar, b.x, nloc, nx); b.st[0] = nloc; b.st[1] = nx; }
;         const unsigned old = xb_add(&bar[XB_XSUB(b.x)], 1u);
;         const unsigned gen = old / nloc;
;         if (old + 1u == (gen + 1u) * nloc) {
;             __builtin_amdgcn_fence(__ATOMIC_RELEASE, "agent");
;             asm volatile("s_waitcnt vmcnt(0)" ::: "memory");
;             const unsigned og = xb_add(&bar[XB_TOP], 1u);
;             const unsigned tg = og / nx;
;             if (og + 1u == (tg + 1u) * nx) xb_add(&bar[XB_TOPGEN], 1u);
;             else XB_SPIN(xb_ld(&bar[XB_TOPGEN]) == tg, bar);
;             __builtin_amdgcn_fence(__ATOMIC_ACQUIRE, "agent");
;             xb_add(&bar[XB_XGEN(b.x)], 1u);
;             asm volatile("s_waitcnt vmcnt(0)" ::: "memory");
;         } else {
;             XB_SPIN(xb_ld(&bar[XB_XGEN(b.x)]) == gen, bar);
;             __builtin_amdgcn_fence(__ATOMIC_ACQUIRE, "agent");
;             asm volatile("s_waitcnt vmcnt(0)" ::: "memory");
;         }
;     }
;     __syncthreads();
; }
.LBB0_661:
	s_cmp_gt_i32 s75, 10
	s_cselect_b64 s[0:1], -1, 0
	s_and_b64 s[2:3], s[8:9], s[0:1]
	s_andn2_b64 vcc, exec, s[2:3]
	s_cbranch_vccnz .LBB0_711
	s_waitcnt vmcnt(0)
	v_cmp_eq_u32_e32 vcc, 0, v189
	s_waitcnt vmcnt(0) lgkmcnt(0)
	s_barrier
	s_and_saveexec_b64 s[4:5], vcc
	s_cbranch_execz .LBB0_710
	v_mov_b32_e32 v0, 0x20430
	ds_read_b32 v0, v0
	s_waitcnt lgkmcnt(0)
	v_cmp_ne_u32_e32 vcc, 0, v0
	s_cbranch_vccz .Lseam_slow_7
	v_readlane_b32 s8, v255, 0
	v_readlane_b32 s2, v254, 4
	v_readlane_b32 s3, v254, 5
	s_and_b32 s8, s8, 63
	s_lshl_b32 s8, s8, 2
	s_add_i32 s8, s8, 0x100
	v_mov_b32_e32 v0, s8
	v_mov_b32_e32 v1, 1
	s_mov_b32 s9, 0
	s_nop 2
	global_atomic_add v0, v1, s[2:3]
.Lseam_spin_7:
	global_load_dword v2, v0, s[2:3] sc1
	s_add_i32 s9, s9, 1
	s_waitcnt vmcnt(0)
	v_cmp_gt_u32_e32 vcc, 12, v2
	s_cbranch_vccz .Lseam_done_7
	s_cmp_gt_u32 s9, 30000
	s_cbranch_scc1 .Lseam_done_7
	s_sleep 1
	s_branch .Lseam_spin_7

; __device__ __forceinline__ unsigned xb_ld(unsigned* p)              { return __hip_atomic_load(p, __ATOMIC_RELAXED, __HIP_MEMORY_SCOPE_AGENT); }
; __device__ __forceinline__ unsigned xb_add(unsigned* p, unsigned v) { return __hip_atomic_fetch_add(p, v, __ATOMIC_RELAXED, __HIP_MEMORY_SCOPE_AGENT); }
; #define XB_SPIN(cond, bar) do { unsigned _sp = 0; while (cond) { __builtin_amdgcn_s_sleep(1); \
;     if ((++_sp & 255u) == 0u) { if (xb_ld(&(bar)[XB_TMO])) break; if (_sp > XB_SPIN_CAP) { atomicAdd(&(bar)[XB_TMO], 1u); break; } } } } while (0)
; __device__ __forceinline__ void xcd_barrier(const XcdBarrier& b) {
;     asm volatile("s_waitcnt vmcnt(0)" ::: "memory");
;     __syncthreads();
;     if (threadIdx.x == 0) {
;         unsigned* bar = b.bar;
;         __builtin_amdgcn_s_waitcnt(0);
;         unsigned nloc = b.st[0], nx = b.st[1];
;         if (nloc == 0u) { xcd_barrier_complete(bar, b.x, nloc, nx); b.st[0] = nloc; b.st[1] = nx; }
;         const unsigned old = xb_add(&bar[XB_XSUB(b.x)], 1u);
;         const unsigned gen = old / nloc;
;         if (old + 1u == (gen + 1u) * nloc) {
;             __builtin_amdgcn_fence(__ATOMIC_RELEASE, "agent");
;             asm volatile("s_waitcnt vmcnt(0)" ::: "memory");
;             const unsigned og = xb_add(&bar[XB_TOP], 1u);
;             const unsigned tg = og / nx;
;             if (og + 1u == (tg + 1u) * nx) xb_add(&bar[XB_TOPGEN], 1u);
;             else XB_SPIN(xb_ld(&bar[XB_TOPGEN]) == tg, bar);
;             __builtin_amdgcn_fence(__ATOMIC_ACQUIRE, "agent");
;             xb_add(&bar[XB_XGEN(b.x)], 1u);
;             asm volatile("s_waitcnt vmcnt(0)" ::: "memory");
;         } else {
;             XB_SPIN(xb_ld(&bar[XB_XGEN(b.x)]) == gen, bar);
;             __builtin_amdgcn_fence(__ATOMIC_ACQUIRE, "agent");
;             asm volatile("s_waitcnt vmcnt(0)" ::: "memory");
;         }
;     }
;     __syncthreads();
; }
.LBB0_740:
	s_cmp_gt_i32 s75, 11
	s_cselect_b64 s[0:1], -1, 0
	s_and_b64 s[2:3], s[6:7], s[0:1]
	s_andn2_b64 vcc, exec, s[2:3]
	s_cbranch_vccnz .LBB0_790
	s_waitcnt vmcnt(0)
	v_cmp_eq_u32_e32 vcc, 0, v189
	s_waitcnt vmcnt(0) lgkmcnt(0)
	s_barrier
	s_and_saveexec_b64 s[4:5], vcc
	s_cbranch_execz .LBB0_789
	v_mov_b32_e32 v0, 0x20430
	ds_read_b32 v0, v0
	s_waitcnt lgkmcnt(0)
	v_cmp_ne_u32_e32 vcc, 0, v0
	s_cbranch_vccz .Lseam_slow_8
	v_readlane_b32 s8, v255, 0
	v_readlane_b32 s2, v254, 4
	v_readlane_b32 s3, v254, 5
	s_and_b32 s8, s8, 63
	s_lshl_b32 s8, s8, 2
	s_add_i32 s8, s8, 0x100
	v_mov_b32_e32 v0, s8
	v_mov_b32_e32 v1, 1
	s_mov_b32 s9, 0
	s_nop 2
	global_atomic_add v0, v1, s[2:3]
.Lseam_spin_8:
	global_load_dword v2, v0, s[2:3] sc1
	s_add_i32 s9, s9, 1
	s_waitcnt vmcnt(0)
	v_cmp_gt_u32_e32 vcc, 16, v2
	s_cbranch_vccz .Lseam_done_8
	s_cmp_gt_u32 s9, 30000
	s_cbranch_scc1 .Lseam_done_8
	s_sleep 1
	s_branch .Lseam_spin_8
